# attention->merge seam arrive-only, wait deferred to merge K-tile 14 of the first unit (first 16 K-tiles are the conv half, independent of attention); conv/KV->Qup arrive is fire-and-forget, waiter che
# speedup vs baseline: 1.0165x; 1.0014x over previous
; __device__ __forceinline__ unsigned xb_ld(unsigned* p)              { return __hip_atomic_load(p, __ATOMIC_RELAXED, __HIP_MEMORY_SCOPE_AGENT); }
; __device__ __forceinline__ unsigned xb_add(unsigned* p, unsigned v) { return __hip_atomic_fetch_add(p, v, __ATOMIC_RELAXED, __HIP_MEMORY_SCOPE_AGENT); }
; #define XB_SPIN(cond, bar) do { unsigned _sp = 0; while (cond) { __builtin_amdgcn_s_sleep(1); \
;     if ((++_sp & 255u) == 0u) { if (xb_ld(&(bar)[XB_TMO])) break; if (_sp > XB_SPIN_CAP) { atomicAdd(&(bar)[XB_TMO], 1u); break; } } } } while (0)
; __device__ __forceinline__ void xcd_barrier(const XcdBarrier& b) {
;     ...
;         const unsigned old = xb_add(&bar[XB_XSUB(b.x)], 1u);
;         const unsigned gen = old / nloc;
;         if (old + 1u == (gen + 1u) * nloc) {
;             __builtin_amdgcn_fence(__ATOMIC_RELEASE, "agent");
;             asm volatile("s_waitcnt vmcnt(0)" ::: "memory");
;             const unsigned og = xb_add(&bar[XB_TOP], 1u);
;             const unsigned tg = og / nx;
;             if (og + 1u == (tg + 1u) * nx) xb_add(&bar[XB_TOPGEN], 1u);
;             else XB_SPIN(xb_ld(&bar[XB_TOPGEN]) == tg, bar);
;             __builtin_amdgcn_fence(__ATOMIC_ACQUIRE, "agent");
;             xb_add(&bar[XB_XGEN(b.x)], 1u);
;             asm volatile("s_waitcnt vmcnt(0)" ::: "memory");
;         } else {
.LBB0_942:
	s_waitcnt vmcnt(0)
	s_waitcnt lgkmcnt(0)
	s_barrier
	s_mov_b64 s[0:1], exec
	v_readlane_b32 s2, v254, 5
	v_readlane_b32 s3, v254, 6
	s_and_b64 s[2:3], s[0:1], s[2:3]
	s_mov_b64 exec, s[2:3]
	s_cbranch_execz .LBB0_994
	s_cmp_lg_u32 s98, 0
	s_cbranch_scc1 .Lfb_orig_3
	v_readlane_b32 s4, v254, 4
	v_readlane_b32 s6, v254, 2
	v_readlane_b32 s7, v254, 3
	s_lshl_b32 s4, s4, 8
	s_add_u32 s4, s6, s4
	s_addc_u32 s5, s7, 0
	v_mov_b32_e32 v0, 0
	v_mov_b32_e32 v1, 1
	global_atomic_add v0, v1, s[4:5] offset:1152
	s_branch .LBB0_994

; #define PG8_BAR __builtin_amdgcn_s_barrier()
; template <class Epi, class Sched, bool ALIGN_EPI = false, bool SP2 = false>
; __device__ __forceinline__ void gemm_phase(PG8_LAS unsigned char* lds, const Gemm g, const Sched& S, const Epi& E) {
;     ...
;         if constexpr (ALIGN_EPI) { if (wr == 0) PG8_BAR; }
;         if constexpr (!Epi::AFTER_DRAIN) { E(acc, cur, wr, wc, fr, fq); S.done(cur); }
;     __device__ __forceinline__ void operator()(const AccT& acc, const Unit& u, int wr, int wc, int fr_, int fq_) const {
;         int fr = fr_, fq = fq_; asm volatile("" : "+v"(fr), "+v"(fq));
;         const int pn = u.pn;
;         bf16_t* const QI = (bf16_t*)(ws + WS_QIMG); const float* const ssq_q = (const float*)(ws + WS_SSQ); const float* const rope = (const float*)(ws + WS_ROPE);
;         float ssv[2][4];
; #pragma unroll
;         for (int ai = 0; ai < 2; ++ai)
; #pragma unroll
;             for (int m = 0; m < 4; ++m) ssv[ai][m] = ssq_q[(size_t)ROW_OF(ai, m)];
.LBB0_1013:
	s_cmp_eq_u32 s100, 0
	s_cbranch_scc1 .Lq_skip
	s_mov_b64 s[4:5], exec
	v_readlane_b32 s100, v254, 5
	v_readlane_b32 s101, v254, 6
	s_and_b64 s[100:101], s[4:5], s[100:101]
	s_mov_b64 exec, s[100:101]
	s_cbranch_execz .Lq_join
	v_mov_b32_e32 v184, 0x70480
	v_mov_b32_e32 v186, 0
.Lq_spin:
	global_load_dword v128, v184, s[90:91] offset:0 sc1
	global_load_dword v129, v184, s[90:91] offset:256 sc1
	global_load_dword v130, v184, s[90:91] offset:512 sc1
	global_load_dword v131, v184, s[90:91] offset:768 sc1
	global_load_dword v132, v184, s[90:91] offset:1024 sc1
	global_load_dword v133, v184, s[90:91] offset:1280 sc1
	global_load_dword v134, v184, s[90:91] offset:1536 sc1
	global_load_dword v135, v184, s[90:91] offset:1792 sc1
	v_add_u32_e32 v186, 1, v186
	s_waitcnt vmcnt(0)
	v_min_u32_e32 v128, v128, v129
	v_min_u32_e32 v130, v130, v131
	v_min_u32_e32 v132, v132, v133
	v_min_u32_e32 v134, v134, v135
	v_min_u32_e32 v128, v128, v130
	v_min_u32_e32 v132, v132, v134
	v_min_u32_e32 v128, v128, v132
	v_cmp_le_u32_e32 vcc, 32, v128
	s_cbranch_vccnz .Lq_join
	v_cmp_gt_u32_e32 vcc, 0x8000, v186
	s_cbranch_vccnz .Lq_spin

; __device__ __forceinline__ unsigned xb_ld(unsigned* p)              { return __hip_atomic_load(p, __ATOMIC_RELAXED, __HIP_MEMORY_SCOPE_AGENT); }
; __device__ __forceinline__ unsigned xb_add(unsigned* p, unsigned v) { return __hip_atomic_fetch_add(p, v, __ATOMIC_RELAXED, __HIP_MEMORY_SCOPE_AGENT); }
; #define XB_SPIN(cond, bar) do { unsigned _sp = 0; while (cond) { __builtin_amdgcn_s_sleep(1); \
;     if ((++_sp & 255u) == 0u) { if (xb_ld(&(bar)[XB_TMO])) break; if (_sp > XB_SPIN_CAP) { atomicAdd(&(bar)[XB_TMO], 1u); break; } } } } while (0)
; __device__ __forceinline__ void xcd_barrier(const XcdBarrier& b) {
;     ...
;         const unsigned old = xb_add(&bar[XB_XSUB(b.x)], 1u);
;         const unsigned gen = old / nloc;
;         if (old + 1u == (gen + 1u) * nloc) {
;             __builtin_amdgcn_fence(__ATOMIC_RELEASE, "agent");
;             asm volatile("s_waitcnt vmcnt(0)" ::: "memory");
;             const unsigned og = xb_add(&bar[XB_TOP], 1u);
;             const unsigned tg = og / nx;
;             if (og + 1u == (tg + 1u) * nx) xb_add(&bar[XB_TOPGEN], 1u);
;             else XB_SPIN(xb_ld(&bar[XB_TOPGEN]) == tg, bar);
;             __builtin_amdgcn_fence(__ATOMIC_ACQUIRE, "agent");
;             xb_add(&bar[XB_XGEN(b.x)], 1u);
;             asm volatile("s_waitcnt vmcnt(0)" ::: "memory");
;         } else {
.LBB0_1234:
	s_cmp_gt_i32 s93, 5
	s_cselect_b64 s[0:1], -1, 0
	s_and_b64 s[2:3], s[2:3], s[0:1]
	s_andn2_b64 vcc, exec, s[2:3]
	s_cbranch_vccnz .LBB0_1288
	s_waitcnt vmcnt(0)
	s_waitcnt lgkmcnt(0)
	s_barrier
	s_mov_b64 s[2:3], exec
	v_readlane_b32 s4, v254, 5
	v_readlane_b32 s5, v254, 6
	s_and_b64 s[4:5], s[2:3], s[4:5]
	s_mov_b64 exec, s[4:5]
	s_cbranch_execz .LBB0_1287
	s_cmp_lg_u32 s98, 0
	s_cbranch_scc1 .Lfb_orig_5
	v_readlane_b32 s4, v254, 4
	v_readlane_b32 s6, v254, 2
	v_readlane_b32 s7, v254, 3
	s_lshl_b32 s4, s4, 8
	s_add_u32 s4, s6, s4
	s_addc_u32 s5, s7, 0
	v_mov_b32_e32 v0, 0
	v_mov_b32_e32 v1, 1
	global_atomic_add v0, v1, s[4:5] offset:1088
	s_branch .LBB0_1287

; __global__ void __launch_bounds__(512, 2) fwd_kernel(Args a) {
;     ...
;     if (IN(5)) {
;         pg8::Gemm g{(const bf16_t*)(P.ws + WS_A2), (const bf16_t*)(P.ws + WS_WM), T, DM, 2048}; pg8::StaticOrder S; S.init(T, DM, G, bx);
;         EpiMerge E{P.ws, P.out};
;         pg8::gemm_phase<EpiMerge, pg8::StaticOrder, true, true>(lds, g, S, E);
.LBB0_1287:
	s_or_b64 exec, exec, s[2:3]
	s_waitcnt lgkmcnt(0)
	s_barrier
	s_cmp_eq_u32 s98, 0
	s_cselect_b32 s100, 1, 0

; template <class Epi, class Sched, bool ALIGN_EPI = false, bool SP2 = false>
; __device__ __forceinline__ void gemm_phase(PG8_LAS unsigned char* lds, const Gemm g, const Sched& S, const Epi& E) {
;     ...
;         for (int t = 0; t < nt; t += 2) {
;             if constexpr (Epi::HAS_MID) { if (t == Epi::MID_T) E.mid(acc, cur, wr, wc, fr, fq); }
;             const bool last = (t == nt - 2);
;             const char* a1 = cA + (size_t)(t + 1) * kstep;
;             const char* a2 = last ? nA : cA + (size_t)(t + 2) * kstep; const char* b2 = last ? nB : cB + (size_t)(t + 2) * kstep;
;             const char* a3 = a2 + kstep; const char* b3 = b2 + kstep;
;             if (last && has_next) S.a_ready(nxt);
.LBB0_1312:
	s_cmp_eq_u32 s100, 0
	s_cbranch_scc1 .Lm5_skip
	s_cmp_lg_u32 s26, 14
	s_cbranch_scc1 .Lm5_skip
	s_mov_b64 s[62:63], exec
	v_readlane_b32 s100, v254, 5
	v_readlane_b32 s101, v254, 6
	s_and_b64 s[100:101], s[62:63], s[100:101]
	s_mov_b64 exec, s[100:101]
	s_cbranch_execz .Lm5_join
	v_readlane_b32 s64, v254, 4
	s_lshl_b32 s64, s64, 8
	s_add_i32 s64, s64, 0x70440
	v_mov_b32_e32 v245, s64
	v_mov_b32_e32 v247, 0
.Lm5_spin:
	global_load_dword v246, v245, s[90:91] sc1
	v_add_u32_e32 v247, 1, v247
	s_waitcnt vmcnt(0)
	v_cmp_le_u32_e32 vcc, 0x60, v246
	s_cbranch_vccnz .Lm5_done
	v_cmp_gt_u32_e32 vcc, 0x8000, v247
	s_cbranch_vccnz .Lm5_spin

; template <class Epi, class Sched, bool ALIGN_EPI = false, bool SP2 = false>
; __device__ __forceinline__ void gemm_phase(PG8_LAS unsigned char* lds, const Gemm g, const Sched& S, const Epi& E) {
;     ...
;         for (int t = 0; t < nt; t += 2) {
;             if constexpr (Epi::HAS_MID) { if (t == Epi::MID_T) E.mid(acc, cur, wr, wc, fr, fq); }
;             const bool last = (t == nt - 2);
;             const char* a1 = cA + (size_t)(t + 1) * kstep;
;             const char* a2 = last ? nA : cA + (size_t)(t + 2) * kstep; const char* b2 = last ? nB : cB + (size_t)(t + 2) * kstep;
;             const char* a3 = a2 + kstep; const char* b3 = b2 + kstep;
;             if (last && has_next) S.a_ready(nxt);
.Lm5_join:
	s_mov_b64 exec, s[62:63]
	s_mov_b32 s100, 0
	s_barrier
